# HGRN combine as 512 extra work-queue items (128-token chunks) behind the attention items; phase 3 and one grid barrier removed
# speedup vs baseline: 1.0152x; 1.0079x over previous
; DI void phase_mixer(const Params& p) {
;     ...
;   for (;;) {
;     __syncthreads();
;     if (threadIdx.x == 0) *sItem = (int)atomicAdd(ctr, 1u);
;     __syncthreads();
;     const int it = *sItem;
;     if (it >= 48 + 2048) break;
;     if (it < 48) hgrn_item(p, it); else attn_item(p, it - 48);
.LBB0_958:
	s_or_b64 exec, exec, s[0:1]
	s_waitcnt lgkmcnt(0)
	s_barrier
	ds_read_b32 v0, v213
	s_waitcnt lgkmcnt(0)
	v_readfirstlane_b32 s12, v0
	s_mov_b64 s[0:1], -1
	s_cmpk_gt_i32 s12, 0x82f
	s_cbranch_scc1 .Lcq_dispatch
	s_cmp_gt_i32 s12, 47
	s_cbranch_scc0 .LBB0_1000
	s_sub_i32 s5, s12, 48
	s_lshl_b32 s3, s5, 5
	s_cmpk_gt_u32 s5, 0x3ff
	s_cbranch_scc0 .LBB0_962
	s_and_b32 s0, s3, 0xe000
	s_lshr_b32 s4, s5, 6
	s_and_b32 s10, s5, 63
	s_add_i32 s6, s0, 0xffff8000
	s_mov_b64 s[0:1], 0

; DI void phase_mixer(const Params& p) {
;     ...
;   for (;;) {
;     __syncthreads();
;     if (threadIdx.x == 0) *sItem = (int)atomicAdd(ctr, 1u);
;     __syncthreads();
;     const int it = *sItem;
;     if (it >= 48 + 2048) break;
;     if (it < 48) hgrn_item(p, it); else attn_item(p, it - 48);
.Lcq_dispatch:
	s_cmpk_gt_i32 s12, 2607
	s_cbranch_scc1 .LBB0_953
	s_and_saveexec_b64 s[0:1], s[84:85]
	s_cbranch_execz .Lcq_go
	v_mov_b32_e32 v0, 0

; DI void phase_combine(const Params& p) {
;   const int lane = threadIdx.x & 63, wave = threadIdx.x >> 6;
;   const unsigned* ofw = (const unsigned*)p.out; const unsigned* obw = (const unsigned*)((const bf16_t*)p.out + (size_t)NTOK * 512);
;   const unsigned* GH = (const unsigned*)(p.ws + WS_GH);
;   bf16_t* OC = (bf16_t*)(p.ws + WS_OCAT);
;   const float w0 = p.hgrn_norm_w[lane * 2], w1 = p.hgrn_norm_w[lane * 2 + 1];
;   for (int tok = blockIdx.x * 8 + wave; tok < NTOK; tok += gridDim.x * 8) {
;     unsigned a[4], b[4], g[4];
; #pragma unroll
;     for (int hh = 0; hh < 4; ++hh) { const size_t idx = ((size_t)tok * 512 + hh * 128 + lane * 2) >> 1; a[hh] = ofw[idx]; b[hh] = obw[idx]; g[hh] = GH[idx]; }
.Lcq_go:
	s_or_b64 exec, exec, s[0:1]
	s_barrier
	s_sub_i32 s3, s12, 0x830
	s_lshl_b32 s3, s3, 7
	s_add_i32 s99, s3, 128
	v_lshrrev_b32_e32 v0, 6, v202
	v_add_u32_e32 v0, s3, v0
	v_and_b32_e32 v4, 0x7e, v203
	v_lshlrev_b32_e32 v1, 2, v4
	global_load_dwordx2 v[2:3], v1, s[46:47]
	v_cmp_lt_i32_e32 vcc, v206, v205
	s_add_u32 s6, s56, 0x4000000
	s_addc_u32 s7, s57, 0
	v_cndmask_b32_e32 v1, v204, v206, vcc
	v_cmp_lt_i32_e32 vcc, v207, v205
	v_lshlrev_b32_e32 v8, 2, v1
	s_add_u32 s8, s58, 0x26000000
	v_cndmask_b32_e32 v1, v204, v207, vcc
	v_cmp_lt_i32_e32 vcc, v211, v205
	v_lshlrev_b32_e32 v9, 2, v1
	s_addc_u32 s9, s59, 0
	v_cndmask_b32_e32 v1, v204, v211, vcc
	v_cmp_lt_i32_e32 vcc, v210, v205
	v_lshlrev_b32_e32 v10, 2, v1
	v_mov_b32_e32 v5, 0
	v_cndmask_b32_e32 v1, v204, v210, vcc
	v_cmp_lt_i32_e32 vcc, v209, v205
	v_lshlrev_b32_e32 v11, 2, v1
	s_mov_b32 s3, 8
	v_cndmask_b32_e32 v1, v204, v209, vcc
	v_cmp_lt_i32_e32 vcc, v208, v205
	v_lshlrev_b32_e32 v12, 2, v1
	s_mov_b64 s[10:11], 0
	v_cndmask_b32_e32 v1, v204, v208, vcc
	v_lshlrev_b32_e32 v13, 2, v1
	v_lshlrev_b32_e32 v4, 1, v4
	s_mov_b64 s[12:13], 0x2a000400
	v_mov_b32_e32 v14, 0x358637bd
	s_mov_b32 s14, 0x800000
	s_mov_b32 s15, 0x2a000000
	s_mov_b32 s16, 0xffff
	v_readfirstlane_b32 s98, v0
	v_ashrrev_i32_e32 v1, 31, v0
	v_lshlrev_b64 v[90:91], 10, v[0:1]
	v_or_b32_e32 v90, v90, v4
	v_lshl_add_u64 v[92:93], s[56:57], 0, v[90:91]
	v_lshl_add_u64 v[94:95], s[6:7], 0, v[90:91]
	v_lshl_add_u64 v[96:97], s[8:9], 0, v[90:91]
	global_load_dword v40, v[92:93], off
	global_load_dword v41, v[92:93], off offset:256
	global_load_dword v42, v[92:93], off offset:512
	global_load_dword v43, v[92:93], off offset:768
	global_load_dword v44, v[94:95], off
	global_load_dword v45, v[94:95], off offset:256
	global_load_dword v46, v[94:95], off offset:512
	global_load_dword v47, v[94:95], off offset:768
	global_load_dword v48, v[96:97], off
	global_load_dword v49, v[96:97], off offset:256
	global_load_dword v50, v[96:97], off offset:512
	global_load_dword v51, v[96:97], off offset:768
	s_waitcnt vmcnt(0)
	s_branch .Lc3_entry

; DI unsigned cvt_pk_bf16(float lo, float hi) { unsigned r; asm("v_cvt_pk_bf16_f32 %0, %1, %2" : "=v"(r) : "v"(lo), "v"(hi)); return r; }
; DI void phase_combine(const Params& p) {
;     ...
;   for (int tok = blockIdx.x * 8 + wave; tok < NTOK; tok += gridDim.x * 8) {
;     unsigned a[4], b[4], g[4];
; #pragma unroll
;     for (int hh = 0; hh < 4; ++hh) { const size_t idx = ((size_t)tok * 512 + hh * 128 + lane * 2) >> 1; a[hh] = ofw[idx]; b[hh] = obw[idx]; g[hh] = GH[idx]; }
; #pragma unroll
;     for (int hh = 0; hh < 4; ++hh) {
;       const float o0 = __uint_as_float(a[hh] << 16) + __uint_as_float(b[hh] << 16), o1 = __uint_as_float(a[hh] & 0xffff0000u) + __uint_as_float(b[hh] & 0xffff0000u);
;       const float ss = wave_sum(o0 * o0 + o1 * o1);
;       const float rstd = rsqrtf(ss * (1.f / 128.f) + EPSN);
;       const float g0 = __uint_as_float(g[hh] << 16), g1 = __uint_as_float(g[hh] & 0xffff0000u);
;       *(unsigned*)(OC + (size_t)tok * 1024 + 512 + hh * 128 + lane * 2) = cvt_pk_bf16(o0 * rstd * w0 * g0, o1 * rstd * w1 * g1);
;     }
;   }
.Lc3_entry:
	v_mov_b32_e32 v52, v40
	v_mov_b32_e32 v53, v41
	v_mov_b32_e32 v54, v42
	v_mov_b32_e32 v55, v43
	v_mov_b32_e32 v56, v44
	v_mov_b32_e32 v57, v45
	v_mov_b32_e32 v58, v46
	v_mov_b32_e32 v59, v47
	v_mov_b32_e32 v60, v48
	v_mov_b32_e32 v61, v49
	v_mov_b32_e32 v62, v50
	v_mov_b32_e32 v63, v51
	v_mov_b32_e32 v100, v0
	v_add_u32_e32 v0, s3, v0
	s_add_i32 s98, s98, s3
	s_cmp_lt_i32 s98, s99
	s_cbranch_scc0 .Lc3_noload
	v_ashrrev_i32_e32 v1, 31, v0
	v_lshlrev_b64 v[90:91], 10, v[0:1]
	v_or_b32_e32 v90, v90, v4
	v_lshl_add_u64 v[92:93], s[56:57], 0, v[90:91]
	v_lshl_add_u64 v[94:95], s[6:7], 0, v[90:91]
	v_lshl_add_u64 v[96:97], s[8:9], 0, v[90:91]
	global_load_dword v40, v[92:93], off
	global_load_dword v41, v[92:93], off offset:256
	global_load_dword v42, v[92:93], off offset:512
	global_load_dword v43, v[92:93], off offset:768
	global_load_dword v44, v[94:95], off
	global_load_dword v45, v[94:95], off offset:256
	global_load_dword v46, v[94:95], off offset:512
	global_load_dword v47, v[94:95], off offset:768
	global_load_dword v48, v[96:97], off
	global_load_dword v49, v[96:97], off offset:256
	global_load_dword v50, v[96:97], off offset:512
	global_load_dword v51, v[96:97], off offset:768
.Lc3_noload:
	v_lshlrev_b32_e32 v64, 16, v52
	v_lshlrev_b32_e32 v76, 16, v56
	v_and_b32_e32 v68, 0xffff0000, v52
	v_and_b32_e32 v80, 0xffff0000, v56
	v_add_f32_e32 v64, v64, v76
	v_add_f32_e32 v68, v68, v80
	v_mul_f32_e32 v72, v64, v64
	v_mul_f32_e32 v76, v68, v68
	v_add_f32_e32 v72, v72, v76
	v_lshlrev_b32_e32 v65, 16, v53
	v_lshlrev_b32_e32 v77, 16, v57
	v_and_b32_e32 v69, 0xffff0000, v53
	v_and_b32_e32 v81, 0xffff0000, v57
	v_add_f32_e32 v65, v65, v77
	v_add_f32_e32 v69, v69, v81
	v_mul_f32_e32 v73, v65, v65
	v_mul_f32_e32 v77, v69, v69
	v_add_f32_e32 v73, v73, v77
	v_lshlrev_b32_e32 v66, 16, v54
	v_lshlrev_b32_e32 v78, 16, v58
	v_and_b32_e32 v70, 0xffff0000, v54
	v_and_b32_e32 v82, 0xffff0000, v58
	v_add_f32_e32 v66, v66, v78
	v_add_f32_e32 v70, v70, v82
	v_mul_f32_e32 v74, v66, v66
	v_mul_f32_e32 v78, v70, v70
	v_add_f32_e32 v74, v74, v78
	v_lshlrev_b32_e32 v67, 16, v55
	v_lshlrev_b32_e32 v79, 16, v59
	v_and_b32_e32 v71, 0xffff0000, v55
	v_and_b32_e32 v83, 0xffff0000, v59
	v_add_f32_e32 v67, v67, v79
	v_add_f32_e32 v71, v71, v83
	v_mul_f32_e32 v75, v67, v67
	v_mul_f32_e32 v79, v71, v71
	v_add_f32_e32 v75, v75, v79
	v_ashrrev_i32_e32 v101, 31, v100
	v_lshlrev_b64 v[98:99], 11, v[100:101]
	v_lshl_add_u64 v[98:99], s[58:59], 0, v[98:99]
	v_lshl_add_u64 v[98:99], v[98:99], 0, v[4:5]
	v_lshl_add_u64 v[98:99], v[98:99], 0, s[12:13]
	ds_bpermute_b32 v76, v8, v72
	ds_bpermute_b32 v77, v8, v73
	ds_bpermute_b32 v78, v8, v74
	ds_bpermute_b32 v79, v8, v75
	s_waitcnt lgkmcnt(3)
	v_add_f32_e32 v72, v72, v76
	s_waitcnt lgkmcnt(2)
	v_add_f32_e32 v73, v73, v77
	s_waitcnt lgkmcnt(1)
	v_add_f32_e32 v74, v74, v78
	s_waitcnt lgkmcnt(0)
	v_add_f32_e32 v75, v75, v79
	ds_bpermute_b32 v76, v9, v72
	ds_bpermute_b32 v77, v9, v73
	ds_bpermute_b32 v78, v9, v74
	ds_bpermute_b32 v79, v9, v75
	s_waitcnt lgkmcnt(3)
	v_add_f32_e32 v72, v72, v76
	s_waitcnt lgkmcnt(2)
	v_add_f32_e32 v73, v73, v77
	s_waitcnt lgkmcnt(1)
	v_add_f32_e32 v74, v74, v78
	s_waitcnt lgkmcnt(0)
	v_add_f32_e32 v75, v75, v79
	ds_bpermute_b32 v76, v10, v72
	ds_bpermute_b32 v77, v10, v73
	ds_bpermute_b32 v78, v10, v74
	ds_bpermute_b32 v79, v10, v75
	s_waitcnt lgkmcnt(3)
	v_add_f32_e32 v72, v72, v76
	s_waitcnt lgkmcnt(2)
	v_add_f32_e32 v73, v73, v77
	s_waitcnt lgkmcnt(1)
	v_add_f32_e32 v74, v74, v78
	s_waitcnt lgkmcnt(0)
	v_add_f32_e32 v75, v75, v79
	ds_bpermute_b32 v76, v11, v72
	ds_bpermute_b32 v77, v11, v73
	ds_bpermute_b32 v78, v11, v74
	ds_bpermute_b32 v79, v11, v75
	s_waitcnt lgkmcnt(3)
	v_add_f32_e32 v72, v72, v76
	s_waitcnt lgkmcnt(2)
	v_add_f32_e32 v73, v73, v77
	s_waitcnt lgkmcnt(1)
	v_add_f32_e32 v74, v74, v78
	s_waitcnt lgkmcnt(0)
	v_add_f32_e32 v75, v75, v79
	ds_bpermute_b32 v76, v12, v72
	ds_bpermute_b32 v77, v12, v73
	ds_bpermute_b32 v78, v12, v74
	ds_bpermute_b32 v79, v12, v75
	s_waitcnt lgkmcnt(3)
	v_add_f32_e32 v72, v72, v76
	s_waitcnt lgkmcnt(2)
	v_add_f32_e32 v73, v73, v77
	s_waitcnt lgkmcnt(1)
	v_add_f32_e32 v74, v74, v78
	s_waitcnt lgkmcnt(0)
	v_add_f32_e32 v75, v75, v79
	ds_bpermute_b32 v76, v13, v72
	ds_bpermute_b32 v77, v13, v73
	ds_bpermute_b32 v78, v13, v74
	ds_bpermute_b32 v79, v13, v75
	s_waitcnt lgkmcnt(3)
	v_add_f32_e32 v72, v72, v76
	s_waitcnt lgkmcnt(2)
	v_add_f32_e32 v73, v73, v77
	s_waitcnt lgkmcnt(1)
	v_add_f32_e32 v74, v74, v78
	s_waitcnt lgkmcnt(0)
	v_add_f32_e32 v75, v75, v79
	v_fmamk_f32 v80, v72, 0x3c000000, v14
	v_mul_f32_e32 v76, 0x4b800000, v80
	v_cmp_gt_f32_e32 vcc, s14, v80
	s_nop 1
	v_cndmask_b32_e32 v80, v80, v76, vcc
	v_rsq_f32_e32 v80, v80
	s_nop 0
	v_mul_f32_e32 v76, 0x45800000, v80
	v_cndmask_b32_e32 v80, v80, v76, vcc
	v_mul_f32_e32 v64, v64, v80
	v_mul_f32_e32 v68, v68, v80
	v_mul_f32_e32 v64, v2, v64
	v_mul_f32_e32 v68, v3, v68
	v_lshlrev_b32_e32 v76, 16, v60
	v_and_b32_e32 v72, 0xffff0000, v60
	v_mul_f32_e32 v64, v64, v76
	v_mul_f32_e32 v68, v68, v72
	v_cvt_pk_bf16_f32 v64, v64, v68
	global_store_dword v[98:99], v64, off
	v_fmamk_f32 v81, v73, 0x3c000000, v14
	v_mul_f32_e32 v77, 0x4b800000, v81
	v_cmp_gt_f32_e32 vcc, s14, v81
	s_nop 1
	v_cndmask_b32_e32 v81, v81, v77, vcc
	v_rsq_f32_e32 v81, v81
	s_nop 0
	v_mul_f32_e32 v77, 0x45800000, v81
	v_cndmask_b32_e32 v81, v81, v77, vcc
	v_mul_f32_e32 v65, v65, v81
	v_mul_f32_e32 v69, v69, v81
	v_mul_f32_e32 v65, v2, v65
	v_mul_f32_e32 v69, v3, v69
	v_lshlrev_b32_e32 v77, 16, v61
	v_and_b32_e32 v73, 0xffff0000, v61
	v_mul_f32_e32 v65, v65, v77
	v_mul_f32_e32 v69, v69, v73
	v_cvt_pk_bf16_f32 v65, v65, v69
	global_store_dword v[98:99], v65, off offset:256
	v_fmamk_f32 v82, v74, 0x3c000000, v14
	v_mul_f32_e32 v78, 0x4b800000, v82
	v_cmp_gt_f32_e32 vcc, s14, v82
	s_nop 1
	v_cndmask_b32_e32 v82, v82, v78, vcc
	v_rsq_f32_e32 v82, v82
	s_nop 0
	v_mul_f32_e32 v78, 0x45800000, v82
	v_cndmask_b32_e32 v82, v82, v78, vcc
	v_mul_f32_e32 v66, v66, v82
	v_mul_f32_e32 v70, v70, v82
	v_mul_f32_e32 v66, v2, v66
	v_mul_f32_e32 v70, v3, v70
	v_lshlrev_b32_e32 v78, 16, v62
	v_and_b32_e32 v74, 0xffff0000, v62
	v_mul_f32_e32 v66, v66, v78
	v_mul_f32_e32 v70, v70, v74
	v_cvt_pk_bf16_f32 v66, v66, v70
	global_store_dword v[98:99], v66, off offset:512
	v_fmamk_f32 v83, v75, 0x3c000000, v14
	v_mul_f32_e32 v79, 0x4b800000, v83
	v_cmp_gt_f32_e32 vcc, s14, v83
	s_nop 1
	v_cndmask_b32_e32 v83, v83, v79, vcc
	v_rsq_f32_e32 v83, v83
	s_nop 0
	v_mul_f32_e32 v79, 0x45800000, v83
	v_cndmask_b32_e32 v83, v83, v79, vcc
	v_mul_f32_e32 v67, v67, v83
	v_mul_f32_e32 v71, v71, v83
	v_mul_f32_e32 v67, v2, v67
	v_mul_f32_e32 v71, v3, v71
	v_lshlrev_b32_e32 v79, 16, v63
	v_and_b32_e32 v75, 0xffff0000, v63
	v_mul_f32_e32 v67, v67, v79
	v_mul_f32_e32 v71, v71, v75
	v_cvt_pk_bf16_f32 v67, v67, v71
	global_store_dword v[98:99], v67, off offset:768
	s_cmp_lt_i32 s98, s99
	s_cbranch_scc1 .Lc3_loop
	s_branch .LBB0_952
; DI unsigned xb_add(unsigned* p, unsigned v) { return __hip_atomic_fetch_add(p, v, __ATOMIC_RELAXED, __HIP_MEMORY_SCOPE_AGENT); }
; DI void xcd_barrier(const XcdBarrier& b) {
;   asm volatile("s_waitcnt vmcnt(0)" ::: "memory");
;   __syncthreads();
;   if (threadIdx.x == 0) {
;     unsigned* bar = b.bar;
;     __builtin_amdgcn_s_waitcnt(0);
;     unsigned nloc = b.st[0], nx = b.st[1];
;     if (nloc == 0u) { xcd_barrier_complete(bar, b.x, nloc, nx); b.st[0] = nloc; b.st[1] = nx; }
;     const unsigned old = xb_add(&bar[XB_XSUB(b.x)], 1u);
.LBB0_1009:
	s_waitcnt vmcnt(0)
	s_barrier
	v_readlane_b32 s48, v236, 12
	v_readlane_b32 s72, v236, 8
	v_readlane_b32 s49, v236, 13
	v_readlane_b32 s70, v236, 11
	v_readlane_b32 s71, v236, 10
	v_readlane_b32 s73, v236, 9
	v_readlane_b32 s74, v236, 1
	v_readlane_b32 s78, v236, 7
	v_readlane_b32 s75, v236, 2
	s_and_saveexec_b64 s[0:1], s[84:85]
	s_cbranch_execz .LBB0_1116
	s_add_i32 s3, 0, 0x20c00
	v_mov_b32_e32 v0, s3
	s_waitcnt vmcnt(0) expcnt(0) lgkmcnt(0)
	ds_read_b32 v2, v0
	s_add_i32 s3, 0, 0x20c04
	v_mov_b32_e32 v0, s3
	ds_read_b32 v0, v0
	s_waitcnt lgkmcnt(1)
	v_cmp_ne_u32_e32 vcc, 0, v2
	s_cbranch_vccnz .LBB0_1080
	s_add_u32 s4, s58, 0x32042300
	s_addc_u32 s5, s59, 0
	s_add_u32 s6, s58, 0x32042500
	s_addc_u32 s7, s59, 0
	s_add_u32 s8, s58, 0x32042600
	s_addc_u32 s9, s59, 0
	s_add_u32 s10, s58, 0x32042700
	s_addc_u32 s11, s59, 0
	s_add_u32 s12, s58, 0x32042800
	s_addc_u32 s13, s59, 0
	s_add_u32 s14, s58, 0x32042900
	s_addc_u32 s15, s59, 0
	s_add_u32 s16, s58, 0x32042a00
	s_addc_u32 s17, s59, 0
	s_add_u32 s18, s58, 0x32042b00
	s_addc_u32 s19, s59, 0
	s_add_u32 s20, s58, 0x32042c00
	s_addc_u32 s21, s59, 0
	s_add_u32 s22, s58, 0x32042d00
	s_addc_u32 s23, s59, 0
	s_add_u32 s24, s58, 0x32042e00
	s_addc_u32 s25, s59, 0
	s_add_u32 s26, s58, 0x32042f00
	s_addc_u32 s27, s59, 0
	s_add_u32 s28, s58, 0x32043000
	s_addc_u32 s29, s59, 0
	s_add_u32 s30, s58, 0x32043100
	s_addc_u32 s31, s59, 0
	s_add_u32 s34, s58, 0x32043200
	s_addc_u32 s35, s59, 0
	s_add_u32 s36, s58, 0x32043300
	s_addc_u32 s37, s59, 0
	s_mul_i32 s3, s77, s71
	s_add_u32 s38, s58, 0x32043400
	s_mul_i32 s3, s3, s76
	s_addc_u32 s39, s59, 0
	s_mov_b32 s33, 1
	v_mov_b32_e32 v16, 0
	s_branch .LBB0_1068
